# mix1a static load balance: blocks whose two poolc tiles have long windows take one kvstate tile, the short-window blocks take three (same tiles, different block assignment)
# speedup vs baseline: 1.0015x; 1.0015x over previous
.LBB0_500:
	s_or_b64 exec, exec, s[0:1]
	s_cmpk_gt_i32 s2, 0x7ff
	s_waitcnt lgkmcnt(0)
	s_barrier
	s_cbranch_scc1 .LBB0_515
	v_xor_b32_e32 v1, v128, v131
	v_lshlrev_b32_e32 v1, 3, v1
	s_movk_i32 s1, 0x1e0
	v_and_b32_e32 v2, 56, v1
	v_and_b32_e32 v1, 0x60, v158
	v_and_or_b32 v4, v153, s1, v138
	v_bitop3_b32 v6, v128, v139, 3 bitop3:0x6c
	s_movk_i32 s0, 0x60
	v_lshlrev_b32_e32 v7, 4, v6
	v_lshlrev_b32_e32 v9, 7, v4
	v_lshlrev_b32_e32 v4, 7, v1
	v_and_b32_e32 v6, 0x1f0, v153
	s_movk_i32 s1, 0x50
	v_bitop3_b32 v24, v4, v6, s0 bitop3:0xf6
	s_movk_i32 s0, 0x70
	v_or_b32_e32 v13, v4, v6
	v_bitop3_b32 v15, v4, v6, 16 bitop3:0xf6
	v_bitop3_b32 v17, v4, v6, 32 bitop3:0xf6
	v_bitop3_b32 v19, v4, v6, 48 bitop3:0xf6
	v_bitop3_b32 v22, v4, v6, 64 bitop3:0xf6
	v_bitop3_b32 v23, v4, v6, s1 bitop3:0xf6
	v_bitop3_b32 v25, v4, v6, s0 bitop3:0xf6
	v_lshlrev_b32_e32 v10, 13, v135
	v_lshl_add_u32 v4, v134, 3, v138
	v_lshlrev_b32_e32 v8, 5, v138
	v_or3_b32 v67, v10, v137, v8
	v_add_u32_e32 v8, 0x60, v4
	v_lshl_or_b32 v6, v134, 11, v10
	v_and_b32_e32 v8, 0x7f, v8
	v_lshl_or_b32 v148, v4, 2, v6
	v_lshl_or_b32 v149, v8, 2, v6
	v_add_u32_e32 v4, 0x70, v4
	v_add_u32_e32 v8, 8, v133
	v_lshlrev_b32_e32 v12, 5, v135
	v_and_b32_e32 v4, 0x7f, v4
	v_and_b32_e32 v8, 0x78, v8
	v_mov_b32_e32 v65, 0
	v_lshl_or_b32 v150, v4, 2, v6
	v_or_b32_e32 v20, v134, v12
	v_lshlrev_b32_e32 v6, 9, v136
	v_lshlrev_b32_e32 v8, 2, v8
	v_or_b32_e32 v21, v136, v12
	v_add_u32_e32 v14, 16, v133
	v_lshlrev_b32_e32 v64, 1, v1
	v_lshlrev_b32_e32 v4, 7, v20
	v_or3_b32 v151, v10, v6, v8
	v_lshlrev_b32_e32 v6, 7, v21
	v_and_b32_e32 v14, 0x78, v14
	v_add_u32_e32 v16, 24, v133
	v_lshlrev_b32_e32 v68, 12, v20
	v_lshlrev_b32_e32 v70, 12, v21
	v_lshl_add_u64 v[20:21], s[50:51], 0, v[64:65]
	s_mov_b64 s[0:1], 0xba00000
	v_lshlrev_b32_e32 v64, 9, v157
	v_lshlrev_b32_e32 v8, 9, v132
	v_lshlrev_b32_e32 v14, 2, v14
	v_and_b32_e32 v16, 0x78, v16
	v_or_b32_e32 v18, 16, v12
	v_lshl_add_u64 v[84:85], v[20:21], 0, s[0:1]
	v_lshl_add_u64 v[20:21], s[50:51], 0, v[64:65]
	v_lshlrev_b32_e32 v64, 1, v2
	v_or3_b32 v160, v10, v8, v14
	v_or_b32_e32 v26, v132, v12
	v_lshlrev_b32_e32 v14, 9, v130
	v_lshlrev_b32_e32 v16, 2, v16
	v_or_b32_e32 v27, v130, v12
	v_or_b32_e32 v28, v18, v134
	v_or_b32_e32 v29, v136, v18
	v_or_b32_e32 v30, v132, v18
	v_or_b32_e32 v31, v130, v18
	v_lshl_add_u64 v[20:21], v[20:21], 0, v[64:65]
	s_mov_b64 s[0:1], 0x1000000
	v_and_b32_e32 v0, 0x7f000, v156
	v_and_b32_e32 v3, 14, v153
	v_lshlrev_b32_e32 v5, 7, v138
	v_lshlrev_b32_e32 v11, 4, v152
	v_lshlrev_b32_e32 v8, 7, v26
	v_or3_b32 v161, v10, v14, v16
	v_lshlrev_b32_e32 v10, 7, v27
	v_lshlrev_b32_e32 v12, 7, v28
	v_lshlrev_b32_e32 v14, 7, v29
	v_lshlrev_b32_e32 v16, 7, v30
	v_lshlrev_b32_e32 v18, 7, v31
	s_add_u32 s33, s50, 0x3a00000
	v_lshl_add_u64 v[86:87], v[20:21], 0, s[0:1]
	v_lshl_add_u64 v[20:21], s[50:51], 0, v[64:65]
	s_mov_b64 s[0:1], 0x1a00000
	v_lshlrev_b32_e32 v66, 3, v138
	v_and_b32_e32 v162, 0x70, v129
	v_mov_b32_e32 v69, v65
	v_mov_b32_e32 v71, v65
	v_lshlrev_b32_e32 v72, 12, v26
	v_mov_b32_e32 v73, v65
	v_lshlrev_b32_e32 v74, 12, v27
	v_mov_b32_e32 v75, v65
	v_lshlrev_b32_e32 v76, 12, v28
	v_mov_b32_e32 v77, v65
	v_lshlrev_b32_e32 v78, 12, v29
	v_mov_b32_e32 v79, v65
	v_lshlrev_b32_e32 v80, 12, v30
	v_mov_b32_e32 v81, v65
	v_lshlrev_b32_e32 v82, 12, v31
	v_mov_b32_e32 v83, v65
	s_addc_u32 s44, s51, 0
	v_lshl_add_u64 v[88:89], v[20:21], 0, s[0:1]
	s_mov_b32 s45, 0xc2fc0000
	s_mov_b32 s46, 0x3f2aaaab
	v_mov_b32_e32 v163, 0x3ecc95a3
	s_mov_b32 s47, 0x3f317218
	s_mov_b32 s52, 0x33800000
	s_mov_b32 s19, 0
	v_lshlrev_b32_e32 v90, 1, v0
	v_lshlrev_b32_e32 v92, 1, v2
	s_mov_b64 s[20:21], 0x40000
	v_add_u32_e32 v164, 0x1000, v129
	s_mov_b64 s[22:23], 0x80000
	v_add_u32_e32 v165, 0x2000, v129
	s_mov_b64 s[24:25], 0xc0000
	v_add_u32_e32 v166, 0x3000, v129
	s_movk_i32 s53, 0x7fff
	v_add_u32_e32 v167, v13, v3
	v_add_u32_e32 v168, v15, v3
	v_add_u32_e32 v169, v17, v3
	v_add_u32_e32 v170, v19, v3
	v_add_u32_e32 v171, v22, v3
	v_add_u32_e32 v172, v23, v3
	v_add_u32_e32 v173, v24, v3
	v_add_u32_e32 v174, v25, v3
	v_add_u32_e32 v175, v7, v9
	v_add_u32_e32 v176, v7, v5
	v_add_u32_e32 v177, v11, v9
	v_add_u32_e32 v178, v11, v5
	s_mov_b32 s54, 0x7060302
	v_lshlrev_b32_e32 v94, 1, v4
	v_lshlrev_b32_e32 v96, 1, v6
	v_lshlrev_b32_e32 v98, 1, v8
	v_lshlrev_b32_e32 v100, 1, v10
	v_lshlrev_b32_e32 v102, 1, v12
	v_lshlrev_b32_e32 v104, 1, v14
	v_lshlrev_b32_e32 v106, 1, v16
	v_lshlrev_b32_e32 v108, 1, v18
	s_mov_b64 s[26:27], 0x4000
	s_mov_b64 s[28:29], 0x8000
	s_mov_b64 s[30:31], 0xc000
	s_mov_b64 s[34:35], 0x10000
	s_movk_i32 s55, 0xf800
	v_mov_b32_e32 v179, 0x42800000
	v_mov_b32_e32 v180, 0x7fc00000
	v_mov_b32_e32 v181, 0xff800000
	s_mov_b32 s56, s2
	s_mov_b32 s99, 0
	s_cmp_eq_u32 s3, 0x200
	s_cbranch_scc0 .Lmy_m1a_gen
	s_add_i32 s65, s2, 0x200
	s_add_i32 s66, s2, 0x400
	s_add_i32 s67, s2, 0x600
	s_xor_b32 s68, s2, 2
	s_add_i32 s68, s68, 0x600
	s_lshr_b32 s69, s2, 1
	s_lshr_b32 s70, s2, 2
	s_xor_b32 s69, s69, s70
	s_and_b32 s69, s69, 1
	s_and_b32 s70, s2, 0x100
	s_cmp_lg_u32 s69, 0
	s_cselect_b32 s71, s67, -1
	s_cselect_b32 s72, s68, -1
	s_mov_b32 s60, s2
	s_mov_b32 s61, s65
	s_mov_b32 s62, s66
	s_mov_b32 s63, s71
	s_mov_b32 s64, s72
	s_cmp_eq_u32 s70, 0
	s_cbranch_scc1 .Lmy_m1a_go
	s_mov_b32 s60, s66
	s_cmp_lg_u32 s69, 0
	s_cselect_b32 s61, s67, s2
	s_cselect_b32 s62, s68, s65
	s_cselect_b32 s63, s2, -1
	s_cselect_b32 s64, s65, -1
.Lmy_m1a_go:
	s_mov_b32 s99, 1
	s_mov_b32 s56, s60
.Lmy_m1a_gen:
	s_branch .LBB0_503
.LBB0_502:
	s_cmp_eq_u32 s99, 0
	s_cbranch_scc1 .Lmy_m1a_stride
	s_cmp_eq_u32 s99, 1
	s_cselect_b32 s56, s61, -1
	s_cmp_eq_u32 s99, 2
	s_cselect_b32 s56, s62, s56
	s_cmp_eq_u32 s99, 3
	s_cselect_b32 s56, s63, s56
	s_cmp_eq_u32 s99, 4
	s_cselect_b32 s56, s64, s56
	s_add_i32 s99, s99, 1
	s_cmp_lt_i32 s56, 0
	s_cbranch_scc1 .LBB0_515
	s_branch .LBB0_503
